# L1 in-proj epilogue (fused q/k norm + rope): 16 dword touches at epilogue start pull all eight blocks' cos/sin rows into L1 so the per-block dwordx4 loads waited with vmcnt(0) hit L1 (on keep_v9)
# baseline (speedup 1.0000x reference)
.LBB0_185:
	v_lshl_add_u32 v195, s47, 8, v188
	v_lshl_or_b32 v162, s48, 8, v192
	s_cmp_lt_i32 s48, 8
	s_mov_b64 s[4:5], -1
	s_cbranch_scc0 .LBB0_204
	v_mov_b32_e32 v231, 0
	v_mov_b32_e32 v230, v195
	v_lshlrev_b32_e32 v230, 7, v230
	v_and_b32_e32 v230, 0x3ff80, v230
	v_lshl_add_u64 v[232:233], v[146:147], 0, v[230:231]
	global_load_dword v234, v[232:233], off
	v_lshl_add_u64 v[232:233], v[156:157], 0, v[230:231]
	global_load_dword v234, v[232:233], off
	v_add_u32_e32 v230, 0x10, v195
	v_lshlrev_b32_e32 v230, 7, v230
	v_and_b32_e32 v230, 0x3ff80, v230
	v_lshl_add_u64 v[232:233], v[146:147], 0, v[230:231]
	global_load_dword v234, v[232:233], off
	v_lshl_add_u64 v[232:233], v[156:157], 0, v[230:231]
	global_load_dword v234, v[232:233], off
	v_add_u32_e32 v230, 0x20, v195
	v_lshlrev_b32_e32 v230, 7, v230
	v_and_b32_e32 v230, 0x3ff80, v230
	v_lshl_add_u64 v[232:233], v[146:147], 0, v[230:231]
	global_load_dword v234, v[232:233], off
	v_lshl_add_u64 v[232:233], v[156:157], 0, v[230:231]
	global_load_dword v234, v[232:233], off
	v_add_u32_e32 v230, 0x30, v195
	v_lshlrev_b32_e32 v230, 7, v230
	v_and_b32_e32 v230, 0x3ff80, v230
	v_lshl_add_u64 v[232:233], v[146:147], 0, v[230:231]
	global_load_dword v234, v[232:233], off
	v_lshl_add_u64 v[232:233], v[156:157], 0, v[230:231]
	global_load_dword v234, v[232:233], off
	v_add_u32_e32 v230, 0x80, v195
	v_lshlrev_b32_e32 v230, 7, v230
	v_and_b32_e32 v230, 0x3ff80, v230
	v_lshl_add_u64 v[232:233], v[146:147], 0, v[230:231]
	global_load_dword v234, v[232:233], off
	v_lshl_add_u64 v[232:233], v[156:157], 0, v[230:231]
	global_load_dword v234, v[232:233], off
	v_add_u32_e32 v230, 0x90, v195
	v_lshlrev_b32_e32 v230, 7, v230
	v_and_b32_e32 v230, 0x3ff80, v230
	v_lshl_add_u64 v[232:233], v[146:147], 0, v[230:231]
	global_load_dword v234, v[232:233], off
	v_lshl_add_u64 v[232:233], v[156:157], 0, v[230:231]
	global_load_dword v234, v[232:233], off
	v_add_u32_e32 v230, 0xa0, v195
	v_lshlrev_b32_e32 v230, 7, v230
	v_and_b32_e32 v230, 0x3ff80, v230
	v_lshl_add_u64 v[232:233], v[146:147], 0, v[230:231]
	global_load_dword v234, v[232:233], off
	v_lshl_add_u64 v[232:233], v[156:157], 0, v[230:231]
	global_load_dword v234, v[232:233], off
	v_add_u32_e32 v230, 0xb0, v195
	v_lshlrev_b32_e32 v230, 7, v230
	v_and_b32_e32 v230, 0x3ff80, v230
	v_lshl_add_u64 v[232:233], v[146:147], 0, v[230:231]
	global_load_dword v234, v[232:233], off
	v_lshl_add_u64 v[232:233], v[156:157], 0, v[230:231]
	global_load_dword v234, v[232:233], off
	s_cmp_lt_i32 s48, 4
	s_cselect_b64 vcc, -1, 0
	s_and_b64 s[4:5], vcc, exec
	s_cselect_b32 s5, s17, s19
	s_cselect_b32 s4, s16, s18
	global_load_dwordx4 v[130:133], v194, s[4:5] offset:16
	global_load_dwordx4 v[134:137], v194, s[4:5]
	v_mov_b32_e32 v0, 0x3e38aa3b
	v_cndmask_b32_e32 v0, 1.0, v0, vcc
	s_cmpk_lt_i32 s47, 0x80
	s_cselect_b64 s[6:7], -1, 0
	s_cmpk_gt_i32 s47, 0x7f
	s_waitcnt vmcnt(0)
	v_pk_mul_f32 v[176:177], v[0:1], v[132:133] op_sel_hi:[0,1]
	v_pk_mul_f32 v[168:169], v[0:1], v[136:137] op_sel_hi:[0,1]
	v_pk_mul_f32 v[170:171], v[0:1], v[134:135] op_sel_hi:[0,1]
	global_load_dwordx4 v[134:137], v194, s[4:5] offset:144
	global_load_dwordx4 v[164:167], v194, s[4:5] offset:128
	v_pk_mul_f32 v[178:179], v[0:1], v[130:131] op_sel_hi:[0,1]
	v_pk_mul_f32 v[130:131], v[128:129], v[128:129]
	v_pk_mul_f32 v[132:133], v[126:127], v[126:127]
	s_waitcnt vmcnt(0)
	v_pk_mul_f32 v[172:173], v[0:1], v[166:167] op_sel_hi:[0,1]
	v_pk_mul_f32 v[166:167], v[0:1], v[134:135] op_sel_hi:[0,1]
	v_pk_mov_b32 v[134:135], v[132:133], v[130:131] op_sel:[1,0]
	v_mov_b32_e32 v133, v131
	v_pk_add_f32 v[130:131], v[134:135], v[132:133]
	v_pk_mul_f32 v[132:133], v[124:125], v[124:125]
	v_pk_mul_f32 v[134:135], v[122:123], v[122:123]
	v_pk_mul_f32 v[174:175], v[0:1], v[164:165] op_sel_hi:[0,1]
	v_pk_mul_f32 v[164:165], v[0:1], v[136:137] op_sel_hi:[0,1]
	v_pk_mov_b32 v[136:137], v[134:135], v[132:133] op_sel:[1,0]
	v_mov_b32_e32 v135, v133
	v_pk_add_f32 v[132:133], v[136:137], v[134:135]
	v_mul_f32_e32 v0, v106, v106
	v_mul_f32_e32 v134, v107, v107
	v_pk_add_f32 v[130:131], v[130:131], v[130:131] op_sel:[0,1] op_sel_hi:[1,0]
	v_pk_add_f32 v[132:133], v[132:133], v[132:133] op_sel:[0,1] op_sel_hi:[1,0]
	v_mov_b32_e32 v131, v0
	v_mov_b32_e32 v133, v134
	v_mul_f32_e32 v0, v111, v111
	v_mul_f32_e32 v135, v108, v108
	v_pk_add_f32 v[130:131], v[130:131], v[132:133]
	v_pk_fma_f32 v[132:133], v[110:111], v[110:111], v[0:1] op_sel_hi:[1,1,0]
	v_mul_f32_e32 v0, v113, v113
	v_mul_f32_e32 v136, v109, v109
	v_mov_b32_e32 v133, v135
	v_pk_fma_f32 v[134:135], v[112:113], v[112:113], v[0:1] op_sel_hi:[1,1,0]
	s_nop 0
	v_mov_b32_e32 v135, v136
	v_pk_add_f32 v[132:133], v[132:133], v[134:135]
	s_nop 0
	v_pk_add_f32 v[130:131], v[130:131], v[132:133]
	s_nop 0
	v_add_f32_e32 v0, v130, v131
	ds_bpermute_b32 v130, v190, v0
	s_waitcnt lgkmcnt(0)
	v_add_f32_e32 v0, v0, v130
	ds_bpermute_b32 v130, v191, v0
	s_waitcnt lgkmcnt(0)
	v_add_f32_e32 v0, v0, v130
	v_fmamk_f32 v0, v0, 0x3c800000, v240
	v_cmp_gt_f32_e32 vcc, s77, v0
	v_mul_f32_e32 v130, 0x4f800000, v0
	s_nop 0
	v_cndmask_b32_e32 v0, v0, v130, vcc
	v_sqrt_f32_e32 v130, v0
	s_nop 0
	v_add_u32_e32 v131, -1, v130
	v_fma_f32 v132, -v131, v130, v0
	v_cmp_ge_f32_e64 s[4:5], 0, v132
	v_add_u32_e32 v132, 1, v130
	s_nop 0
	v_cndmask_b32_e64 v131, v130, v131, s[4:5]
	v_fma_f32 v130, -v132, v130, v0
	v_cmp_lt_f32_e64 s[4:5], 0, v130
	s_nop 1
	v_cndmask_b32_e64 v130, v131, v132, s[4:5]
	v_mul_f32_e32 v131, 0x37800000, v130
	v_cndmask_b32_e32 v130, v130, v131, vcc
	v_cmp_class_f32_e32 vcc, v0, v241
	s_nop 1
	v_cndmask_b32_e32 v0, v130, v0, vcc
	v_div_scale_f32 v130, s[4:5], v0, v0, 1.0
	v_rcp_f32_e32 v131, v130
	s_nop 0
	v_fma_f32 v132, -v130, v131, 1.0
	v_fmac_f32_e32 v131, v132, v131
	v_div_scale_f32 v132, vcc, 1.0, v0, 1.0
	v_mul_f32_e32 v133, v132, v131
	v_fma_f32 v134, -v130, v133, v132
	v_fmac_f32_e32 v133, v134, v131
	v_fma_f32 v130, -v130, v133, v132
	v_div_fmas_f32 v130, v130, v131, v133
	v_div_fixup_f32 v0, v130, v0, 1.0
	v_pk_mul_f32 v[130:131], v[126:127], v[0:1] op_sel_hi:[1,0]
	v_pk_mul_f32 v[132:133], v[128:129], v[0:1] op_sel_hi:[1,0]
	v_pk_mul_f32 v[148:149], v[110:111], v[0:1] op_sel_hi:[1,0]
	v_pk_mul_f32 v[150:151], v[112:113], v[0:1] op_sel_hi:[1,0]
	v_pk_mul_f32 v[136:137], v[168:169], v[132:133]
	v_pk_mul_f32 v[134:135], v[170:171], v[130:131]
	v_pk_mul_f32 v[130:131], v[122:123], v[0:1] op_sel_hi:[1,0]
	v_pk_mul_f32 v[132:133], v[124:125], v[0:1] op_sel_hi:[1,0]
	v_pk_mul_f32 v[180:181], v[172:173], v[150:151]
	v_pk_mul_f32 v[182:183], v[174:175], v[148:149]
	v_pk_mul_f32 v[148:149], v[106:107], v[0:1] op_sel_hi:[1,0]
	v_pk_mul_f32 v[150:151], v[108:109], v[0:1] op_sel_hi:[1,0]
	v_pk_mul_f32 v[132:133], v[176:177], v[132:133]
	v_pk_mul_f32 v[130:131], v[178:179], v[130:131]
	v_pk_mul_f32 v[184:185], v[164:165], v[150:151]
	v_pk_mul_f32 v[186:187], v[166:167], v[148:149]
	s_cbranch_scc1 .LBB0_188
	v_lshlrev_b32_e32 v0, 7, v195
	v_and_b32_e32 v0, 0x3e780, v0
	v_lshl_add_u64 v[148:149], v[146:147], 0, v[0:1]
	global_load_dwordx4 v[196:199], v[148:149], off offset:16
	global_load_dwordx4 v[200:203], v[148:149], off
	v_lshl_add_u64 v[148:149], v[156:157], 0, v[0:1]
	global_load_dwordx4 v[204:207], v[148:149], off offset:16
	global_load_dwordx4 v[208:211], v[148:149], off
	s_waitcnt vmcnt(0)
	v_pk_mul_f32 v[150:151], v[182:183], v[208:209]
	v_pk_mul_f32 v[148:149], v[180:181], v[210:211]
	v_pk_fma_f32 v[212:213], v[134:135], v[200:201], v[150:151] neg_lo:[0,0,1] neg_hi:[0,0,1]
	v_pk_mul_f32 v[134:135], v[134:135], v[208:209]
	v_pk_fma_f32 v[214:215], v[136:137], v[202:203], v[148:149] neg_lo:[0,0,1] neg_hi:[0,0,1]
	v_pk_mul_f32 v[136:137], v[136:137], v[210:211]
	v_pk_fma_f32 v[182:183], v[182:183], v[200:201], v[134:135]
	v_pk_mul_f32 v[134:135], v[184:185], v[206:207]
	v_pk_mul_f32 v[148:149], v[186:187], v[204:205]
	v_pk_fma_f32 v[180:181], v[180:181], v[202:203], v[136:137]
	v_pk_fma_f32 v[136:137], v[132:133], v[198:199], v[134:135] neg_lo:[0,0,1] neg_hi:[0,0,1]
	v_pk_fma_f32 v[134:135], v[130:131], v[196:197], v[148:149] neg_lo:[0,0,1] neg_hi:[0,0,1]
	v_pk_mul_f32 v[132:133], v[132:133], v[206:207]
	v_pk_mul_f32 v[130:131], v[130:131], v[204:205]
	v_pk_fma_f32 v[184:185], v[184:185], v[198:199], v[132:133]
	v_pk_fma_f32 v[186:187], v[186:187], v[196:197], v[130:131]
	v_mov_b64_e32 v[130:131], v[134:135]
	v_mov_b64_e32 v[132:133], v[136:137]
	v_mov_b64_e32 v[134:135], v[212:213]
	v_mov_b64_e32 v[136:137], v[214:215]
